# GEMM K-loop: s_nop after each m0 write replaced by ordering the address add between the m0 write and the LDS-DMA
# baseline (speedup 1.0000x reference)
; #define LDA(dst, b, h) for (int m = 0; m < 4; ++m) for (int k = 0; k < 2; ++k) \
;     dst[m][k] = *reinterpret_cast<const bf16x8*>(SA(b, h) + lds_byte(wr * 64 + m * 16 + fr, k * 32 + fq * 8))
; #define LDB(dst, b, h) for (int n = 0; n < 2; ++n) for (int k = 0; k < 2; ++k) \
;     dst[n][k] = *reinterpret_cast<const bf16x8*>(SB(b, h) + lds_byte(wc * 32 + n * 16 + fr, k * 32 + fq * 8))
; #define MMA(ai, bj, At_, Bt_) do { __builtin_amdgcn_s_setprio(1); \
;     for (int m = 0; m < 4; ++m) for (int n = 0; n < 2; ++n) for (int k = 0; k < 2; ++k) \
;       acc[ai][bj][m][n] = __builtin_amdgcn_mfma_f32_16x16x32_bf16(Bt_[n][k], At_[m][k], acc[ai][bj][m][n], 0, 0, 0); \
;     __builtin_amdgcn_s_setprio(0); } while (0)
; #define WAIT_V(n) asm volatile("s_waitcnt vmcnt(" #n ")" ::: "memory")
; #define WAIT_L(n) asm volatile("s_waitcnt lgkmcnt(" #n ")" ::: "memory")
; #define BAR __builtin_amdgcn_s_barrier()
; #define SCHED __builtin_amdgcn_sched_barrier(0)
; #define STG(P, PTR, LD, O0) do { const bf16_t* _g = (PTR); \
;     __builtin_amdgcn_global_load_lds((const unsigned*)(_g + O0), (lds_u32*)((P) + swave * 1024), 16, 0, 0); \
;     __builtin_amdgcn_global_load_lds((const unsigned*)(_g + (size_t)64 * (LD) + O0), (lds_u32*)((P) + swave * 1024 + 8192), 16, 0, 0); } while (0)
; #define LDA(dst, b, h) for (int m = 0; m < 4; ++m) for (int k = 0; k < 2; ++k) \
;     dst[m][k] = *reinterpret_cast<const bf16x8*>(SA(b, h) + lds_byte(wr * 64 + m * 16 + fr, k * 32 + fq * 8))
; #define LDB(dst, b, h) for (int n = 0; n < 2; ++n) for (int k = 0; k < 2; ++k) \
;     dst[n][k] = *reinterpret_cast<const bf16x8*>(SB(b, h) + lds_byte(wc * 32 + n * 16 + fr, k * 32 + fq * 8))
; #define WAIT_V(n) asm volatile("s_waitcnt vmcnt(" #n ")" ::: "memory")
; __device__ __forceinline__ void gemm_stream(int swave, const GemmJob& J, char* shm, int vb, int G) {
;     ...
;       LDB(B0, 0, 0); SCHED; LDA(At, 0, 0); STGA(SA(1, 1), cA, cA1, t + 1, 1);
;       WAIT_L(8); BAR; WAIT_L(0); MMA(0, 0, At, B0); BAR; SCHED;
;       LDB(B1, 0, 1); STG(SB(0, 0), b2, ldb, offB0);
;       BAR; WAIT_L(0); MMA(0, 1, At, B1); BAR;
;       LDA(At, 0, 1); STGA(SA(0, 0), xA, xA1, k2, 0);
;       BAR; WAIT_L(0); MMA(1, 0, At, B0); BAR; SCHED;
;       STG(SB(0, 1), b2 + hB, ldb, offB0);
;       WAIT_V(6); BAR; MMA(1, 1, At, B1); BAR;
;       LDB(B0, 1, 0); SCHED; LDA(At, 1, 0); STGA(SA(0, 1), xA, xA1, k2, 1);
.LBB0_729:
	ds_read_b128 v[164:167], v139
	ds_read_b128 v[168:171], v139 offset:1024
	ds_read_b128 v[172:175], v139 offset:2048
	ds_read_b128 v[176:179], v139 offset:3072
	s_cmp_eq_u32 s49, s29
	s_cselect_b64 s[68:69], -1, 0
	s_and_b64 s[64:65], s[68:69], exec
	s_cselect_b32 s52, s10, s8
	s_cselect_b32 s64, s11, s9
	s_add_i32 s33, s2, 2
	s_and_b64 s[68:69], s[68:69], exec
	s_cselect_b32 s71, s15, s21
	s_cselect_b32 s70, s14, s20
	s_cselect_b32 s68, 0, s33
	s_cselect_b32 s65, s12, s16
	s_cselect_b32 s66, s13, s17
	s_or_b32 s2, s2, 1
	s_cmp_lt_u32 s2, s36
	s_cselect_b64 vcc, -1, 0
	s_and_b64 s[2:3], vcc, exec
	s_cselect_b32 s3, 0, s36
	s_cselect_b32 s2, s38, s37
	s_not_b32 s3, s3
	s_add_i32 s94, s3, s29
	s_and_b64 s[72:73], vcc, exec
	s_cselect_b32 s3, s9, s17
	s_cselect_b32 s69, s8, s16
	s_lshl_b64 s[72:73], s[94:95], 7
	s_add_u32 s69, s69, s72
	s_addc_u32 s74, s3, s73
	s_mov_b32 s3, s95
	s_lshl_b64 s[72:73], s[2:3], 8
	s_add_u32 s72, s69, s72
	v_cndmask_b32_e32 v2, v138, v0, vcc
	s_addc_u32 s73, s74, s73
	s_add_i32 m0, s42, 0xc000
	s_lshl_b64 s[2:3], s[2:3], 7
	v_lshlrev_b64 v[212:213], 1, v[2:3]
	s_add_u32 s2, s72, s2
	v_lshl_add_u64 v[214:215], s[72:73], 0, v[212:213]
	s_addc_u32 s3, s73, s3
	ds_read_b128 v[180:183], v144
	ds_read_b128 v[184:187], v144 offset:1024
	ds_read_b128 v[188:191], v145
	ds_read_b128 v[192:195], v145 offset:1024
	ds_read_b128 v[196:199], v159
	ds_read_b128 v[200:203], v159 offset:1024
	ds_read_b128 v[204:207], v160
	ds_read_b128 v[208:211], v160 offset:1024
	global_load_lds_dwordx4 v[214:215], off
	s_add_i32 m0, s42, 0xe000
	v_lshl_add_u64 v[212:213], s[2:3], 0, v[212:213]
	global_load_lds_dwordx4 v[212:213], off
	s_waitcnt lgkmcnt(8)
	s_barrier
	s_waitcnt lgkmcnt(0)
	v_mfma_f32_16x16x32_bf16 v[128:131], v[164:167], v[180:183], v[128:131]
	v_mfma_f32_16x16x32_bf16 v[124:127], v[172:175], v[180:183], v[124:127]
	v_mfma_f32_16x16x32_bf16 v[120:123], v[164:167], v[188:191], v[120:123]
	v_mfma_f32_16x16x32_bf16 v[116:119], v[172:175], v[188:191], v[116:119]
	v_mfma_f32_16x16x32_bf16 v[104:107], v[164:167], v[196:199], v[104:107]
	v_mfma_f32_16x16x32_bf16 v[100:103], v[172:175], v[196:199], v[100:103]
	v_mfma_f32_16x16x32_bf16 v[88:91], v[164:167], v[204:207], v[88:91]
	v_mfma_f32_16x16x32_bf16 v[84:87], v[172:175], v[204:207], v[84:87]
	v_mfma_f32_16x16x32_bf16 v[128:131], v[168:171], v[184:187], v[128:131]
	v_mfma_f32_16x16x32_bf16 v[124:127], v[176:179], v[184:187], v[124:127]
	v_mfma_f32_16x16x32_bf16 v[120:123], v[168:171], v[192:195], v[120:123]
	v_mfma_f32_16x16x32_bf16 v[116:119], v[176:179], v[192:195], v[116:119]
	v_mfma_f32_16x16x32_bf16 v[104:107], v[168:171], v[200:203], v[104:107]
	v_mfma_f32_16x16x32_bf16 v[100:103], v[176:179], v[200:203], v[100:103]
	v_mfma_f32_16x16x32_bf16 v[88:91], v[168:171], v[208:211], v[88:91]
	v_mfma_f32_16x16x32_bf16 v[84:87], v[176:179], v[208:211], v[84:87]
	s_barrier
	s_add_u32 s2, s70, s0
	s_mov_b32 m0, s43
	v_lshl_add_u64 v[228:229], s[70:71], 0, v[136:137]
	s_addc_u32 s3, s71, s1
	ds_read_b128 v[212:215], v161
	ds_read_b128 v[216:219], v161 offset:1024
	ds_read_b128 v[220:223], v161 offset:2048
	ds_read_b128 v[224:227], v161 offset:3072
	global_load_lds_dwordx4 v[228:229], off
	s_mov_b32 m0, s44
	v_lshl_add_u64 v[230:231], s[2:3], 0, v[136:137]
	global_load_lds_dwordx4 v[230:231], off
	s_barrier
	s_waitcnt lgkmcnt(0)
	v_mfma_f32_16x16x32_bf16 v[112:115], v[212:215], v[180:183], v[112:115]
	v_mfma_f32_16x16x32_bf16 v[108:111], v[220:223], v[180:183], v[108:111]
	s_cmp_lt_u32 s68, s36
	s_cselect_b64 vcc, -1, 0
	v_mfma_f32_16x16x32_bf16 v[96:99], v[212:215], v[188:191], v[96:99]
	s_and_b64 s[70:71], vcc, exec
	s_cselect_b32 s70, s38, s37
	v_mfma_f32_16x16x32_bf16 v[92:95], v[220:223], v[188:191], v[92:95]
	s_sub_i32 s69, s68, s36
	s_min_u32 s94, s68, s69
	v_mfma_f32_16x16x32_bf16 v[80:83], v[212:215], v[196:199], v[80:83]
	s_and_b64 s[72:73], vcc, exec
	s_cselect_b32 s69, s64, s66
	v_mfma_f32_16x16x32_bf16 v[76:79], v[220:223], v[196:199], v[76:79]
	s_cselect_b32 s71, s52, s65
	s_lshl_b64 s[72:73], s[94:95], 7
	v_mfma_f32_16x16x32_bf16 v[72:75], v[212:215], v[204:207], v[72:75]
	v_cndmask_b32_e32 v2, v138, v0, vcc
	s_add_u32 s72, s71, s72
	v_mfma_f32_16x16x32_bf16 v[68:71], v[220:223], v[204:207], v[68:71]
	s_mov_b32 s71, s95
	v_mfma_f32_16x16x32_bf16 v[112:115], v[216:219], v[184:187], v[112:115]
	s_addc_u32 s73, s69, s73
	v_mfma_f32_16x16x32_bf16 v[108:111], v[224:227], v[184:187], v[108:111]
	v_lshlrev_b64 v[232:233], 1, v[2:3]
	v_mfma_f32_16x16x32_bf16 v[96:99], v[216:219], v[192:195], v[96:99]
	s_lshl_b64 s[70:71], s[70:71], 7
	v_mfma_f32_16x16x32_bf16 v[92:95], v[224:227], v[192:195], v[92:95]
	v_lshl_add_u64 v[234:235], s[72:73], 0, v[232:233]
	v_mfma_f32_16x16x32_bf16 v[80:83], v[216:219], v[200:203], v[80:83]
	s_add_u32 s72, s72, s70
	v_mfma_f32_16x16x32_bf16 v[76:79], v[224:227], v[200:203], v[76:79]
	s_mov_b32 m0, s42
	v_mfma_f32_16x16x32_bf16 v[72:75], v[216:219], v[208:211], v[72:75]
	s_addc_u32 s73, s73, s71
	v_mfma_f32_16x16x32_bf16 v[68:71], v[224:227], v[208:211], v[68:71]
	s_barrier
	ds_read_b128 v[180:183], v144 offset:16384
	ds_read_b128 v[184:187], v144 offset:17408
	ds_read_b128 v[188:191], v145 offset:16384
	ds_read_b128 v[192:195], v145 offset:17408
	ds_read_b128 v[196:199], v159 offset:16384
	ds_read_b128 v[200:203], v159 offset:17408
	ds_read_b128 v[204:207], v160 offset:16384
	ds_read_b128 v[208:211], v160 offset:17408
	global_load_lds_dwordx4 v[234:235], off
	s_mov_b32 m0, s39
	v_lshl_add_u64 v[234:235], s[72:73], 0, v[232:233]
	global_load_lds_dwordx4 v[234:235], off
	s_barrier
; #define LDA(dst, b, h) for (int m = 0; m < 4; ++m) for (int k = 0; k < 2; ++k) \
;     dst[m][k] = *reinterpret_cast<const bf16x8*>(SA(b, h) + lds_byte(wr * 64 + m * 16 + fr, k * 32 + fq * 8))
; #define LDB(dst, b, h) for (int n = 0; n < 2; ++n) for (int k = 0; k < 2; ++k) \
;     dst[n][k] = *reinterpret_cast<const bf16x8*>(SB(b, h) + lds_byte(wc * 32 + n * 16 + fr, k * 32 + fq * 8))
; #define MMA(ai, bj, At_, Bt_) do { __builtin_amdgcn_s_setprio(1); \
;     for (int m = 0; m < 4; ++m) for (int n = 0; n < 2; ++n) for (int k = 0; k < 2; ++k) \
;       acc[ai][bj][m][n] = __builtin_amdgcn_mfma_f32_16x16x32_bf16(Bt_[n][k], At_[m][k], acc[ai][bj][m][n], 0, 0, 0); \
;     __builtin_amdgcn_s_setprio(0); } while (0)
; #define WAIT_V(n) asm volatile("s_waitcnt vmcnt(" #n ")" ::: "memory")
; #define WAIT_L(n) asm volatile("s_waitcnt lgkmcnt(" #n ")" ::: "memory")
; #define BAR __builtin_amdgcn_s_barrier()
; #define SCHED __builtin_amdgcn_sched_barrier(0)
; #define STG(P, PTR, LD, O0) do { const bf16_t* _g = (PTR); \
;     __builtin_amdgcn_global_load_lds((const unsigned*)(_g + O0), (lds_u32*)((P) + swave * 1024), 16, 0, 0); \
;     __builtin_amdgcn_global_load_lds((const unsigned*)(_g + (size_t)64 * (LD) + O0), (lds_u32*)((P) + swave * 1024 + 8192), 16, 0, 0); } while (0)
; #define LDA(dst, b, h) for (int m = 0; m < 4; ++m) for (int k = 0; k < 2; ++k) \
;     dst[m][k] = *reinterpret_cast<const bf16x8*>(SA(b, h) + lds_byte(wr * 64 + m * 16 + fr, k * 32 + fq * 8))
; #define LDB(dst, b, h) for (int n = 0; n < 2; ++n) for (int k = 0; k < 2; ++k) \
;     dst[n][k] = *reinterpret_cast<const bf16x8*>(SB(b, h) + lds_byte(wc * 32 + n * 16 + fr, k * 32 + fq * 8))
; #define WAIT_V(n) asm volatile("s_waitcnt vmcnt(" #n ")" ::: "memory")
; #define WAIT_L(n) asm volatile("s_waitcnt lgkmcnt(" #n ")" ::: "memory")
; __device__ __forceinline__ void gemm_stream(int swave, const GemmJob& J, char* shm, int vb, int G) {
;     ...
;       BAR; WAIT_L(0); MMA(1, 0, At, B0); BAR; SCHED;
;       STG(SB(0, 1), b2 + hB, ldb, offB0);
;       WAIT_V(6); BAR; MMA(1, 1, At, B1); BAR;
;       LDB(B0, 1, 0); SCHED; LDA(At, 1, 0); STGA(SA(0, 1), xA, xA1, k2, 1);
;       WAIT_L(8); BAR; WAIT_L(0); MMA(0, 0, At, B0); BAR; SCHED;
;       LDB(B1, 1, 1); STG(SB(1, 0), b3, ldb, offB0);
;       BAR; WAIT_L(0); MMA(0, 1, At, B1); BAR;
;       LDA(At, 1, 1); STGA(SA(1, 0), xA, xA1, k2 + 1, 0);
	s_waitcnt lgkmcnt(0)
	v_mfma_f32_16x16x32_bf16 v[64:67], v[164:167], v[180:183], v[64:67]
	v_mfma_f32_16x16x32_bf16 v[60:63], v[172:175], v[180:183], v[60:63]
	v_mfma_f32_16x16x32_bf16 v[56:59], v[164:167], v[188:191], v[56:59]
	v_mfma_f32_16x16x32_bf16 v[52:55], v[172:175], v[188:191], v[52:55]
	v_mfma_f32_16x16x32_bf16 v[40:43], v[164:167], v[196:199], v[40:43]
	v_mfma_f32_16x16x32_bf16 v[36:39], v[172:175], v[196:199], v[36:39]
	v_mfma_f32_16x16x32_bf16 v[24:27], v[164:167], v[204:207], v[24:27]
	v_mfma_f32_16x16x32_bf16 v[20:23], v[172:175], v[204:207], v[20:23]
	v_mfma_f32_16x16x32_bf16 v[64:67], v[168:171], v[184:187], v[64:67]
	v_mfma_f32_16x16x32_bf16 v[60:63], v[176:179], v[184:187], v[60:63]
	v_mfma_f32_16x16x32_bf16 v[56:59], v[168:171], v[192:195], v[56:59]
	v_mfma_f32_16x16x32_bf16 v[52:55], v[176:179], v[192:195], v[52:55]
	v_mfma_f32_16x16x32_bf16 v[40:43], v[168:171], v[200:203], v[40:43]
	v_mfma_f32_16x16x32_bf16 v[36:39], v[176:179], v[200:203], v[36:39]
	v_mfma_f32_16x16x32_bf16 v[24:27], v[168:171], v[208:211], v[24:27]
	v_mfma_f32_16x16x32_bf16 v[20:23], v[176:179], v[208:211], v[20:23]
	s_barrier
	s_add_u32 s2, s2, s0
	s_addc_u32 s3, s3, s1
	v_lshl_add_u64 v[234:235], s[2:3], 0, v[136:137]
	s_add_u32 s2, s2, s0
	s_mov_b32 m0, s45
	s_addc_u32 s3, s3, s1
	global_load_lds_dwordx4 v[234:235], off
	s_mov_b32 m0, s46
	v_lshl_add_u64 v[236:237], s[2:3], 0, v[136:137]
	global_load_lds_dwordx4 v[236:237], off
	s_waitcnt vmcnt(6)
	s_barrier
	v_mfma_f32_16x16x32_bf16 v[48:51], v[212:215], v[180:183], v[48:51]
	v_mfma_f32_16x16x32_bf16 v[44:47], v[220:223], v[180:183], v[44:47]
	v_mfma_f32_16x16x32_bf16 v[32:35], v[212:215], v[188:191], v[32:35]
	v_mfma_f32_16x16x32_bf16 v[28:31], v[220:223], v[188:191], v[28:31]
	v_mfma_f32_16x16x32_bf16 v[16:19], v[212:215], v[196:199], v[16:19]
	v_mfma_f32_16x16x32_bf16 v[12:15], v[220:223], v[196:199], v[12:15]
	v_mfma_f32_16x16x32_bf16 v[8:11], v[212:215], v[204:207], v[8:11]
	v_mfma_f32_16x16x32_bf16 v[4:7], v[220:223], v[204:207], v[4:7]
	v_mfma_f32_16x16x32_bf16 v[48:51], v[216:219], v[184:187], v[48:51]
	v_mfma_f32_16x16x32_bf16 v[44:47], v[224:227], v[184:187], v[44:47]
	v_mfma_f32_16x16x32_bf16 v[32:35], v[216:219], v[192:195], v[32:35]
	v_mfma_f32_16x16x32_bf16 v[28:31], v[224:227], v[192:195], v[28:31]
	v_mfma_f32_16x16x32_bf16 v[16:19], v[216:219], v[200:203], v[16:19]
	v_mfma_f32_16x16x32_bf16 v[12:15], v[224:227], v[200:203], v[12:15]
	v_mfma_f32_16x16x32_bf16 v[8:11], v[216:219], v[208:211], v[8:11]
	v_mfma_f32_16x16x32_bf16 v[4:7], v[224:227], v[208:211], v[4:7]
	s_barrier
	ds_read_b128 v[164:167], v162
	ds_read_b128 v[168:171], v162 offset:1024
	ds_read_b128 v[172:175], v162 offset:2048
	ds_read_b128 v[176:179], v162 offset:3072
	s_add_u32 s2, s72, s70
	s_addc_u32 s3, s73, s71
	v_lshl_add_u64 v[212:213], s[2:3], 0, v[232:233]
	s_add_u32 s2, s2, s70
	s_mov_b32 m0, s47
	s_addc_u32 s3, s3, s71
	ds_read_b128 v[180:183], v144 offset:32768
	ds_read_b128 v[184:187], v144 offset:33792
	ds_read_b128 v[188:191], v145 offset:32768
	ds_read_b128 v[192:195], v145 offset:33792
	ds_read_b128 v[196:199], v159 offset:32768
	ds_read_b128 v[200:203], v159 offset:33792
	ds_read_b128 v[204:207], v160 offset:32768
	ds_read_b128 v[208:211], v160 offset:33792
	global_load_lds_dwordx4 v[212:213], off
	s_mov_b32 m0, s48
	v_lshl_add_u64 v[212:213], s[2:3], 0, v[232:233]
	global_load_lds_dwordx4 v[212:213], off
	s_waitcnt lgkmcnt(8)
	s_barrier
	s_waitcnt lgkmcnt(0)
	v_mfma_f32_16x16x32_bf16 v[128:131], v[164:167], v[180:183], v[128:131]
	v_mfma_f32_16x16x32_bf16 v[124:127], v[172:175], v[180:183], v[124:127]
	v_mfma_f32_16x16x32_bf16 v[120:123], v[164:167], v[188:191], v[120:123]
	v_mfma_f32_16x16x32_bf16 v[116:119], v[172:175], v[188:191], v[116:119]
	v_mfma_f32_16x16x32_bf16 v[104:107], v[164:167], v[196:199], v[104:107]
	v_mfma_f32_16x16x32_bf16 v[100:103], v[172:175], v[196:199], v[100:103]
	v_mfma_f32_16x16x32_bf16 v[88:91], v[164:167], v[204:207], v[88:91]
	v_mfma_f32_16x16x32_bf16 v[84:87], v[172:175], v[204:207], v[84:87]
	v_mfma_f32_16x16x32_bf16 v[128:131], v[168:171], v[184:187], v[128:131]
	v_mfma_f32_16x16x32_bf16 v[124:127], v[176:179], v[184:187], v[124:127]
	v_mfma_f32_16x16x32_bf16 v[120:123], v[168:171], v[192:195], v[120:123]
	v_mfma_f32_16x16x32_bf16 v[116:119], v[176:179], v[192:195], v[116:119]
	v_mfma_f32_16x16x32_bf16 v[104:107], v[168:171], v[200:203], v[104:107]
	v_mfma_f32_16x16x32_bf16 v[100:103], v[176:179], v[200:203], v[100:103]
	v_mfma_f32_16x16x32_bf16 v[88:91], v[168:171], v[208:211], v[88:91]
	v_mfma_f32_16x16x32_bf16 v[84:87], v[176:179], v[208:211], v[84:87]
	s_barrier
	v_lshl_add_u64 v[228:229], v[228:229], 0, s[22:23]
	s_add_i32 m0, s42, 0x18000
	ds_read_b128 v[212:215], v163
	ds_read_b128 v[216:219], v163 offset:1024
	ds_read_b128 v[220:223], v163 offset:2048
	ds_read_b128 v[224:227], v163 offset:3072
	global_load_lds_dwordx4 v[228:229], off
	s_add_i32 m0, s42, 0x1a000
	v_lshl_add_u64 v[228:229], v[230:231], 0, s[22:23]
	global_load_lds_dwordx4 v[228:229], off
	s_barrier
; #define LDA(dst, b, h) for (int m = 0; m < 4; ++m) for (int k = 0; k < 2; ++k) \
;     dst[m][k] = *reinterpret_cast<const bf16x8*>(SA(b, h) + lds_byte(wr * 64 + m * 16 + fr, k * 32 + fq * 8))
; #define MMA(ai, bj, At_, Bt_) do { __builtin_amdgcn_s_setprio(1); \
;     for (int m = 0; m < 4; ++m) for (int n = 0; n < 2; ++n) for (int k = 0; k < 2; ++k) \
;       acc[ai][bj][m][n] = __builtin_amdgcn_mfma_f32_16x16x32_bf16(Bt_[n][k], At_[m][k], acc[ai][bj][m][n], 0, 0, 0); \
;     __builtin_amdgcn_s_setprio(0); } while (0)
; #define WAIT_V(n) asm volatile("s_waitcnt vmcnt(" #n ")" ::: "memory")
; #define WAIT_L(n) asm volatile("s_waitcnt lgkmcnt(" #n ")" ::: "memory")
; #define BAR __builtin_amdgcn_s_barrier()
; #define SCHED __builtin_amdgcn_sched_barrier(0)
; #define STG(P, PTR, LD, O0) do { const bf16_t* _g = (PTR); \
;     __builtin_amdgcn_global_load_lds((const unsigned*)(_g + O0), (lds_u32*)((P) + swave * 1024), 16, 0, 0); \
;     __builtin_amdgcn_global_load_lds((const unsigned*)(_g + (size_t)64 * (LD) + O0), (lds_u32*)((P) + swave * 1024 + 8192), 16, 0, 0); } while (0)
; #define LDA(dst, b, h) for (int m = 0; m < 4; ++m) for (int k = 0; k < 2; ++k) \
;     dst[m][k] = *reinterpret_cast<const bf16x8*>(SA(b, h) + lds_byte(wr * 64 + m * 16 + fr, k * 32 + fq * 8))
; #define MMA(ai, bj, At_, Bt_) do { __builtin_amdgcn_s_setprio(1); \
;     for (int m = 0; m < 4; ++m) for (int n = 0; n < 2; ++n) for (int k = 0; k < 2; ++k) \
;       acc[ai][bj][m][n] = __builtin_amdgcn_mfma_f32_16x16x32_bf16(Bt_[n][k], At_[m][k], acc[ai][bj][m][n], 0, 0, 0); \
;     __builtin_amdgcn_s_setprio(0); } while (0)
; #define WAIT_V(n) asm volatile("s_waitcnt vmcnt(" #n ")" ::: "memory")
; #define WAIT_L(n) asm volatile("s_waitcnt lgkmcnt(" #n ")" ::: "memory")
; #define BAR __builtin_amdgcn_s_barrier()
; #define SCHED __builtin_amdgcn_sched_barrier(0)
; __device__ __forceinline__ void gemm_stream(int swave, const GemmJob& J, char* shm, int vb, int G) {
;     ...
;       BAR; WAIT_L(0); MMA(0, 1, At, B1); BAR;
;       LDA(At, 1, 1); STGA(SA(1, 0), xA, xA1, k2 + 1, 0);
;       BAR; WAIT_L(0); MMA(1, 0, At, B0); BAR; SCHED;
;       STG(SB(1, 1), b3 + hB, ldb, offB0);
;       WAIT_V(6); BAR; MMA(1, 1, At, B1); BAR;
	s_waitcnt lgkmcnt(0)
	v_mfma_f32_16x16x32_bf16 v[112:115], v[212:215], v[180:183], v[112:115]
	v_mfma_f32_16x16x32_bf16 v[108:111], v[220:223], v[180:183], v[108:111]
	s_or_b32 s68, s68, 1
	s_cmp_lt_u32 s68, s36
	v_mfma_f32_16x16x32_bf16 v[96:99], v[212:215], v[188:191], v[96:99]
	s_cselect_b64 vcc, -1, 0
	s_and_b64 s[2:3], vcc, exec
	v_mfma_f32_16x16x32_bf16 v[92:95], v[220:223], v[188:191], v[92:95]
	s_cselect_b32 s69, s38, s37
	s_sub_i32 s2, s68, s36
	v_mfma_f32_16x16x32_bf16 v[80:83], v[212:215], v[196:199], v[80:83]
	s_min_u32 s94, s68, s2
	s_and_b64 s[2:3], vcc, exec
	v_mfma_f32_16x16x32_bf16 v[76:79], v[220:223], v[196:199], v[76:79]
	s_cselect_b32 s64, s64, s66
	s_cselect_b32 s52, s52, s65
	v_mfma_f32_16x16x32_bf16 v[72:75], v[212:215], v[204:207], v[72:75]
	s_lshl_b64 s[2:3], s[94:95], 7
	v_cndmask_b32_e32 v2, v138, v0, vcc
	v_mfma_f32_16x16x32_bf16 v[68:71], v[220:223], v[204:207], v[68:71]
	s_add_u32 s2, s52, s2
	v_mfma_f32_16x16x32_bf16 v[112:115], v[216:219], v[184:187], v[112:115]
	s_addc_u32 s3, s64, s3
	v_mfma_f32_16x16x32_bf16 v[108:111], v[224:227], v[184:187], v[108:111]
	v_lshlrev_b64 v[228:229], 1, v[2:3]
	v_mfma_f32_16x16x32_bf16 v[96:99], v[216:219], v[192:195], v[96:99]
	s_lshl_b32 s52, s69, 7
	v_mfma_f32_16x16x32_bf16 v[92:95], v[224:227], v[192:195], v[92:95]
	v_lshl_add_u64 v[230:231], s[2:3], 0, v[228:229]
	v_mfma_f32_16x16x32_bf16 v[80:83], v[216:219], v[200:203], v[80:83]
	s_add_u32 s2, s2, s52
	v_mfma_f32_16x16x32_bf16 v[76:79], v[224:227], v[200:203], v[76:79]
	s_mov_b32 m0, s54
	v_mfma_f32_16x16x32_bf16 v[72:75], v[216:219], v[208:211], v[72:75]
	s_addc_u32 s3, s3, 0
	v_mfma_f32_16x16x32_bf16 v[68:71], v[224:227], v[208:211], v[68:71]
	s_barrier
	ds_read_b128 v[180:183], v144 offset:49152
	ds_read_b128 v[184:187], v144 offset:50176
	ds_read_b128 v[188:191], v145 offset:49152
	ds_read_b128 v[192:195], v145 offset:50176
	ds_read_b128 v[196:199], v159 offset:49152
	ds_read_b128 v[200:203], v159 offset:50176
	ds_read_b128 v[204:207], v160 offset:49152
	ds_read_b128 v[208:211], v160 offset:50176
	global_load_lds_dwordx4 v[230:231], off
	s_mov_b32 m0, s55
	v_lshl_add_u64 v[228:229], s[2:3], 0, v[228:229]
	global_load_lds_dwordx4 v[228:229], off
	s_barrier
	s_waitcnt lgkmcnt(0)
	v_mfma_f32_16x16x32_bf16 v[64:67], v[164:167], v[180:183], v[64:67]
	v_mfma_f32_16x16x32_bf16 v[60:63], v[172:175], v[180:183], v[60:63]
	v_mfma_f32_16x16x32_bf16 v[56:59], v[164:167], v[188:191], v[56:59]
	v_mfma_f32_16x16x32_bf16 v[52:55], v[172:175], v[188:191], v[52:55]
	v_mfma_f32_16x16x32_bf16 v[40:43], v[164:167], v[196:199], v[40:43]
	v_mfma_f32_16x16x32_bf16 v[36:39], v[172:175], v[196:199], v[36:39]
	v_mfma_f32_16x16x32_bf16 v[24:27], v[164:167], v[204:207], v[24:27]
	v_mfma_f32_16x16x32_bf16 v[20:23], v[172:175], v[204:207], v[20:23]
	v_mfma_f32_16x16x32_bf16 v[64:67], v[168:171], v[184:187], v[64:67]
	v_mfma_f32_16x16x32_bf16 v[60:63], v[176:179], v[184:187], v[60:63]
	v_mfma_f32_16x16x32_bf16 v[56:59], v[168:171], v[192:195], v[56:59]
	v_mfma_f32_16x16x32_bf16 v[52:55], v[176:179], v[192:195], v[52:55]
	v_mfma_f32_16x16x32_bf16 v[40:43], v[168:171], v[200:203], v[40:43]
	v_mfma_f32_16x16x32_bf16 v[36:39], v[176:179], v[200:203], v[36:39]
	v_mfma_f32_16x16x32_bf16 v[24:27], v[168:171], v[208:211], v[24:27]
	v_mfma_f32_16x16x32_bf16 v[20:23], v[176:179], v[208:211], v[20:23]
	s_barrier
	s_add_i32 m0, s42, 0x1c000
	v_lshl_add_u64 v[164:165], v[234:235], 0, s[22:23]
	global_load_lds_dwordx4 v[164:165], off
	s_add_i32 m0, s42, 0x1e000
	v_lshl_add_u64 v[164:165], v[236:237], 0, s[22:23]
	global_load_lds_dwordx4 v[164:165], off
	s_waitcnt vmcnt(6)
	s_barrier
	v_mfma_f32_16x16x32_bf16 v[48:51], v[212:215], v[180:183], v[48:51]
	v_mfma_f32_16x16x32_bf16 v[44:47], v[220:223], v[180:183], v[44:47]
	s_add_i32 s29, s29, 2
	v_mfma_f32_16x16x32_bf16 v[32:35], v[212:215], v[188:191], v[32:35]
	s_add_u32 s20, s20, 0x100
	v_mfma_f32_16x16x32_bf16 v[28:31], v[220:223], v[188:191], v[28:31]
	s_addc_u32 s21, s21, 0
	v_mfma_f32_16x16x32_bf16 v[16:19], v[212:215], v[196:199], v[16:19]
	s_cmp_ge_u32 s33, s49
	v_mfma_f32_16x16x32_bf16 v[12:15], v[220:223], v[196:199], v[12:15]
	s_mov_b32 s2, s33
	v_mfma_f32_16x16x32_bf16 v[8:11], v[212:215], v[204:207], v[8:11]
	v_mfma_f32_16x16x32_bf16 v[4:7], v[220:223], v[204:207], v[4:7]
	v_mfma_f32_16x16x32_bf16 v[48:51], v[216:219], v[184:187], v[48:51]
	v_mfma_f32_16x16x32_bf16 v[44:47], v[224:227], v[184:187], v[44:47]
	v_mfma_f32_16x16x32_bf16 v[32:35], v[216:219], v[192:195], v[32:35]
	v_mfma_f32_16x16x32_bf16 v[28:31], v[224:227], v[192:195], v[28:31]
	v_mfma_f32_16x16x32_bf16 v[16:19], v[216:219], v[200:203], v[16:19]
	v_mfma_f32_16x16x32_bf16 v[12:15], v[224:227], v[200:203], v[12:15]
	v_mfma_f32_16x16x32_bf16 v[8:11], v[216:219], v[208:211], v[8:11]
	v_mfma_f32_16x16x32_bf16 v[4:7], v[224:227], v[208:211], v[4:7]
	s_barrier
; __device__ __forceinline__ unsigned pk2(float lo, float hi) { f32x2_t v = {lo, hi}; bf16x2_t b = __builtin_convertvector(v, bf16x2_t); return __builtin_bit_cast(unsigned, b); }
; #define WAIT_V(n) asm volatile("s_waitcnt vmcnt(" #n ")" ::: "memory")
; #define BAR __builtin_amdgcn_s_barrier()
; #define WAIT_V(n) asm volatile("s_waitcnt vmcnt(" #n ")" ::: "memory")
; #define BAR __builtin_amdgcn_s_barrier()
; __device__ __forceinline__ void gemm_stream(int swave, const GemmJob& J, char* shm, int vb, int G) {
;     ...
;     {
;       bf16_t* C = (bf16_t*)((char*)J.c0 + (size_t)cg * J.strideC);
; #pragma unroll
;       for (int ai = 0; ai < 2; ++ai)
; #pragma unroll
;         for (int m = 0; m < 4; ++m)
; #pragma unroll
;           for (int bj = 0; bj < 2; ++bj) {
;             const f32x4 v0 = acc[ai][bj][m][0], v1 = acc[ai][bj][m][1];
;             uint4 o; o.x = pk2(v0[0], v0[1]); o.y = pk2(v0[2], v0[3]); o.z = pk2(v1[0], v1[1]); o.w = pk2(v1[2], v1[3]);
;             *(uint4*)(C + (size_t)(cbrow + ai * 128 + wr * 64 + m * 16 + fr) * J.ldc + cbcol + bj * 128 + wc * 32 + fq * 8) = o;
;           }
;     }
;     if (!has_next) break;
; #pragma unroll
;     for (int a_ = 0; a_ < 2; ++a_)
; #pragma unroll
;       for (int b_ = 0; b_ < 2; ++b_)
; #pragma unroll
;         for (int m = 0; m < 4; ++m)
; #pragma unroll
;           for (int n = 0; n < 2; ++n) acc[a_][b_][m][n] = (f32x4){0.f, 0.f, 0.f, 0.f};
;     id = nid; cg = ng; cbrow = nbrow; cbcol = nbcol; cA = nA; cA1 = nA1; cB = nB;
;   }
;   WAIT_V(0);
;   if (wr == 0) BAR;
	s_cbranch_scc0 .LBB0_729
	v_add_u32_e32 v164, s5, v1
	s_ashr_i32 s5, s4, 31
	s_lshl_b64 s[2:3], s[4:5], 1
	v_ashrrev_i32_e32 v2, 31, v164
	s_add_u32 s2, s50, s2
	v_cvt_pk_bf16_f32 v128, v128, v129
	v_cvt_pk_bf16_f32 v129, v130, v131
	v_cvt_pk_bf16_f32 v130, v124, v125
	v_mul_lo_u32 v2, v2, s18
	v_mad_u64_u32 v[124:125], s[4:5], v164, s18, 0
	s_addc_u32 s3, s51, s3
	v_add_u32_e32 v125, v125, v2
	v_lshl_add_u64 v[124:125], v[124:125], 1, s[2:3]
	v_mov_b32_e32 v141, v3
	v_lshl_add_u64 v[124:125], v[124:125], 0, v[140:141]
	v_mov_b32_e32 v143, v3
	v_lshl_add_u64 v[124:125], v[124:125], 0, v[142:143]
	s_lshl_b32 s2, s18, 5
	s_mov_b32 s3, 0
	s_mul_i32 s4, s18, 0xa0
	s_mov_b32 s5, 0
	v_cvt_pk_bf16_f32 v112, v112, v113
	v_cvt_pk_bf16_f32 v113, v114, v115
	v_cvt_pk_bf16_f32 v114, v108, v109
	v_cvt_pk_bf16_f32 v115, v110, v111
	global_store_dwordx4 v[124:125], v[112:115], off offset:256
	v_cvt_pk_bf16_f32 v131, v126, v127
	v_cvt_pk_bf16_f32 v96, v96, v97
	v_lshl_add_u64 v[112:113], v[124:125], 0, s[2:3]
	v_cvt_pk_bf16_f32 v97, v98, v99
	v_cvt_pk_bf16_f32 v98, v92, v93
	v_cvt_pk_bf16_f32 v99, v94, v95
	global_store_dwordx4 v[124:125], v[128:131], off
	global_store_dwordx4 v[112:113], v[96:99], off offset:256
	v_cvt_pk_bf16_f32 v108, v120, v121
	v_cvt_pk_bf16_f32 v109, v122, v123
	v_lshl_add_u64 v[96:97], v[112:113], 0, s[2:3]
	v_cvt_pk_bf16_f32 v110, v116, v117
	v_cvt_pk_bf16_f32 v111, v118, v119
	v_cvt_pk_bf16_f32 v80, v80, v81
	v_cvt_pk_bf16_f32 v81, v82, v83
	v_cvt_pk_bf16_f32 v82, v76, v77
	v_cvt_pk_bf16_f32 v83, v78, v79
	global_store_dwordx4 v[112:113], v[108:111], off
	global_store_dwordx4 v[96:97], v[80:83], off offset:256
	v_cvt_pk_bf16_f32 v64, v64, v65
	v_cvt_pk_bf16_f32 v65, v66, v67
	v_lshl_add_u64 v[80:81], v[96:97], 0, s[2:3]
	v_cvt_pk_bf16_f32 v66, v60, v61
	v_lshl_add_u64 v[60:61], v[80:81], 0, s[4:5]
	v_cvt_pk_bf16_f32 v72, v72, v73
	v_cvt_pk_bf16_f32 v73, v74, v75
	v_cvt_pk_bf16_f32 v74, v68, v69
	v_cvt_pk_bf16_f32 v67, v62, v63
	v_cvt_pk_bf16_f32 v92, v104, v105
	v_cvt_pk_bf16_f32 v93, v106, v107
	v_cvt_pk_bf16_f32 v94, v100, v101
	v_cvt_pk_bf16_f32 v95, v102, v103
	v_cvt_pk_bf16_f32 v76, v88, v89
	v_cvt_pk_bf16_f32 v77, v90, v91
	v_cvt_pk_bf16_f32 v78, v84, v85
	v_cvt_pk_bf16_f32 v79, v86, v87
	v_cvt_pk_bf16_f32 v75, v70, v71
	v_cvt_pk_bf16_f32 v48, v48, v49
	v_cvt_pk_bf16_f32 v49, v50, v51
	v_cvt_pk_bf16_f32 v50, v44, v45
	v_cvt_pk_bf16_f32 v51, v46, v47
	global_store_dwordx4 v[96:97], v[92:95], off
	global_store_dwordx4 v[80:81], v[76:79], off
	global_store_dwordx4 v[80:81], v[72:75], off offset:256
	global_store_dwordx4 v[60:61], v[48:51], off offset:256
	v_cvt_pk_bf16_f32 v32, v32, v33
	v_cvt_pk_bf16_f32 v33, v34, v35
	v_lshl_add_u64 v[48:49], v[60:61], 0, s[2:3]
	v_cvt_pk_bf16_f32 v34, v28, v29
	v_cvt_pk_bf16_f32 v35, v30, v31
	global_store_dwordx4 v[60:61], v[64:67], off
	global_store_dwordx4 v[48:49], v[32:35], off offset:256
	v_cvt_pk_bf16_f32 v44, v56, v57
	v_cvt_pk_bf16_f32 v45, v58, v59
	v_lshl_add_u64 v[32:33], v[48:49], 0, s[2:3]
	v_cvt_pk_bf16_f32 v46, v52, v53
	v_cvt_pk_bf16_f32 v47, v54, v55
	v_cvt_pk_bf16_f32 v16, v16, v17
	v_cvt_pk_bf16_f32 v17, v18, v19
	v_cvt_pk_bf16_f32 v18, v12, v13
	v_cvt_pk_bf16_f32 v19, v14, v15
	global_store_dwordx4 v[48:49], v[44:47], off
	global_store_dwordx4 v[32:33], v[16:19], off offset:256
	v_cvt_pk_bf16_f32 v28, v40, v41
	v_cvt_pk_bf16_f32 v29, v42, v43
	v_lshl_add_u64 v[16:17], v[32:33], 0, s[2:3]
	v_cvt_pk_bf16_f32 v30, v36, v37
	v_cvt_pk_bf16_f32 v31, v38, v39
	v_cvt_pk_bf16_f32 v12, v24, v25
	v_cvt_pk_bf16_f32 v13, v26, v27
	v_cvt_pk_bf16_f32 v14, v20, v21
	v_cvt_pk_bf16_f32 v15, v22, v23
	v_cvt_pk_bf16_f32 v8, v8, v9
	v_cvt_pk_bf16_f32 v9, v10, v11
	v_cvt_pk_bf16_f32 v10, v4, v5
	v_cvt_pk_bf16_f32 v11, v6, v7
	s_and_b64 vcc, exec, s[6:7]
	s_mov_b64 s[2:3], s[14:15]
	s_mov_b64 s[16:17], s[12:13]
	s_mov_b64 s[8:9], s[10:11]
	s_mov_b32 s4, s56
	s_mov_b32 s5, s28
	global_store_dwordx4 v[32:33], v[28:31], off
	global_store_dwordx4 v[16:17], v[12:15], off
	global_store_dwordx4 v[16:17], v[8:11], off offset:256
	s_cbranch_vccz .LBB0_726
	s_waitcnt vmcnt(0)
	s_movk_i32 s66, 0x100
	v_cmp_gt_u32_e32 vcc, s66, v135
	s_and_saveexec_b64 s[0:1], vcc
	s_cbranch_execz .LBB0_733
	s_barrier
